# grid barriers: wave 1 prefetches the next phase's code into L2 (one dword per 128-B line, PC-forward) while wave 0 runs the barrier protocol
# speedup vs baseline: 1.0091x; 1.0007x over previous
; #define G1_PL() { pg8::Gemm g{(const bf16_t*)(ws + WS_PB), (const bf16_t*)(ws + WS_WPL), T, DM, PLE, PLE}; pg8::StaticOrder S; S.init(T, DM, G, (int)blockIdx.x); \
;       pg8::EpiPl E{(bf16_t*)(ws + WS_PL), DM}; pg8::gemm_phase<pg8::EpiPl, pg8::StaticOrder, true, true>(lds, g, S, E); }
;     __host__ __device__ bool next(int i, Unit& u) const {
;         const long L = (long)i * G + c; if (L >= nwg) return false;
;         int wgid = (int)L; { const int q = nwg / NXCD, r = nwg % NXCD, xcd = wgid % NXCD, off = wgid / NXCD; wgid = (xcd < r ? xcd * (q + 1) : r * (q + 1) + (xcd - r) * q) + off; }
;         const int nig = WGM * nN, gid = wgid / nig, fm = gid * WGM, gsz = (nM - fm) < WGM ? (nM - fm) : WGM;
;         u.pm = fm + ((wgid % nig) % gsz); u.pn = (wgid % nig) / gsz; return true;
; __global__ void __launch_bounds__(NTHREADS, 2) fwd_megakernel(Args a) {
;     ...
;     xcd_barrier(bar);
;     ...
;     if (blockIdx.x & 1) G1_PL();
.LBB0_146:
	s_or_b64 exec, exec, s[0:1]
	v_readfirstlane_b32 s98, v254
	s_lshr_b32 s98, s98, 6
	s_cmp_lg_u32 s98, 1
	s_cbranch_scc1 .Lpf_skip_0
	s_getpc_b64 s[100:101]
	v_and_b32_e32 v110, 63, v254
	v_lshlrev_b32_e32 v110, 7, v110
	global_load_dword v111, v110, s[100:101]
	s_add_u32 s100, s100, 0x2000
	s_addc_u32 s101, s101, 0
	global_load_dword v111, v110, s[100:101]
	s_add_u32 s100, s100, 0x2000
	s_addc_u32 s101, s101, 0
	global_load_dword v111, v110, s[100:101]
	s_add_u32 s100, s100, 0x2000
	s_addc_u32 s101, s101, 0
	global_load_dword v111, v110, s[100:101]
	s_waitcnt vmcnt(0)
.Lpf_skip_0:
	s_add_u32 s54, s82, 0x3000000
	s_addc_u32 s55, s83, 0
	s_bitcmp0_b32 s69, 0
	s_cselect_b64 s[4:5], -1, 0
	s_and_b64 vcc, exec, s[4:5]
	s_waitcnt lgkmcnt(0)
	s_barrier
	s_cbranch_vccnz .LBB0_169
	v_mov_b32_e32 v8, v254
	s_cmpk_gt_i32 s69, 0xff
	v_readfirstlane_b32 s18, v8
	s_cbranch_scc1 .LBB0_169
	s_ashr_i32 s21, s69, 31
	s_lshr_b32 s0, s21, 29
	s_add_i32 s2, s69, s0
	s_and_b32 s0, s2, -8
	s_sub_i32 s3, s69, s0
	s_cmp_gt_i32 s3, -1
	s_cbranch_scc0 .LBB0_150
	s_lshl_b32 s9, s3, 5
	s_cbranch_execz .LBB0_151
	s_branch .LBB0_152

; #define PG8_LAS __attribute__((address_space(3)))
; template <class Epi, class Sched, bool ALIGN_EPI = false, bool SP2 = false>
; __device__ __forceinline__ void gemm_phase(PG8_LAS unsigned char* lds, const Gemm g, const Sched& S, const Epi& E) {
;     int tid_ = threadIdx.x; asm volatile("" : "+v"(tid_));
;     const int tid = tid_, wid = __builtin_amdgcn_readfirstlane(tid >> 6), lane = tid & 63, wr = wid >> 2, wc = wid & 3, fr = lane & 15, fq = lane >> 4;
;     const int K = g.K, nt = K / BK;
;     unsigned voffA[2], voffB[2];
; #pragma unroll
;     for (int i = 0; i < 2; ++i) { int R, C; stage_rc(tid * 16 + i * 8192, R, C); const int Rb = Epi::PERM ? ((R & ~31) + perm32(R & 31)) : R;
;         voffA[i] = (unsigned)(R * g.lda + C) * 2u; voffB[i] = (unsigned)(Rb * K + C) * 2u; }
;     const size_t kstep = (size_t)(BK * 2);
;     const size_t hstepB = (size_t)HALF * K * 2, hstepA = (size_t)HALF * g.lda * 2;
;     const size_t tstepB = 2 * hstepB, tstepA = 2 * hstepA;
;     const unsigned ldsw = (unsigned)wid * 1024u;
;     const int aoff = lds_byte(wr * 64 + fr, fq * 8), boff = lds_byte(wc * 32 + fr, fq * 8);
;     ...
;     Unit cur, nxt; int ui = 0;
;     if (!S.next(0, cur)) return;
;     f32x4 acc[2][2][4][2];
; #pragma unroll
;     for (int a = 0; a < 2; ++a)
; #pragma unroll
;         for (int b = 0; b < 2; ++b)
; #pragma unroll
;             for (int m = 0; m < 4; ++m)
; #pragma unroll
;                 for (int n = 0; n < 2; ++n) acc[a][b][m][n] = (f32x4){0.f, 0.f, 0.f, 0.f};
;     bf16x8 At[4][2], B0[2][2], B1[2][2];
;     const char* cA = (const char*)g.A + (size_t)cur.pm * tstepA; const char* cB = (const char*)g.Bt + (size_t)cur.pn * tstepB;
;     S.a_ready(cur);
;     if constexpr (SP2) {
;         PG8_STAGE(PG8_SB(0, 0), cB, voffB); PG8_STAGE(PG8_SB(0, 1), cB + hstepB, voffB); PG8_STAGE(PG8_SA(0, 0), cA, voffA); PG8_STAGE(PG8_SA(0, 1), cA + hstepA, voffA);
;         if (wr == 1) PG8_BAR;
;         PG8_WAIT_V(2); PG8_BAR;
;         PG8_STAGE(PG8_SB(1, 0), cB + kstep, voffB); PG8_STAGE(PG8_SA(1, 0), cA + kstep, voffA); PG8_STAGE(PG8_SB(1, 1), cB + hstepB + kstep, voffB);
;         PG8_WAIT_V(6); PG8_BAR;
;     } else {
;         PG8_STAGE(PG8_SB(0, 0), cB, voffB); PG8_STAGE(PG8_SA(0, 0), cA, voffA); PG8_STAGE(PG8_SB(0, 1), cB + hstepB, voffB); PG8_STAGE(PG8_SA(0, 1), cA + hstepA, voffA);
;         if (wr == 1) PG8_BAR;
;         PG8_WAIT_V(4); PG8_BAR;
.LBB0_292:
	s_or_b64 exec, exec, s[0:1]
	v_readfirstlane_b32 s98, v254
	s_lshr_b32 s98, s98, 6
	s_cmp_lg_u32 s98, 1
	s_cbranch_scc1 .Lpf_skip_1
	s_getpc_b64 s[100:101]
	v_and_b32_e32 v110, 63, v254
	v_lshlrev_b32_e32 v110, 7, v110
	global_load_dword v111, v110, s[100:101]
	s_add_u32 s100, s100, 0x2000
	s_addc_u32 s101, s101, 0
	global_load_dword v111, v110, s[100:101]
	s_waitcnt vmcnt(0)
.Lpf_skip_1:
	s_add_u32 s64, s82, 0x9800000
	s_addc_u32 s65, s83, 0
	v_mov_b32_e32 v10, v254
	s_waitcnt lgkmcnt(0)
	s_barrier
	s_cmpk_gt_i32 s69, 0x1bf
	v_readfirstlane_b32 s0, v10
	s_cbranch_scc1 .LBB0_310
	v_lshlrev_b32_e32 v0, 4, v10
	v_add_u32_e32 v1, 0x2000, v0
	v_ashrrev_i32_e32 v2, 31, v1
	v_lshrrev_b32_e32 v2, 22, v2
	v_add_u32_e32 v2, v1, v2
	v_ashrrev_i32_e32 v8, 10, v2
	v_mul_i32_i24_e32 v2, 0x400, v8
	v_sub_u32_e32 v1, v1, v2
	v_lshrrev_b32_e32 v2, 4, v1
	v_bitop3_b32 v1, v2, v1, 32 bitop3:0x6c
	v_ashrrev_i32_e32 v2, 31, v1
	v_lshrrev_b32_e32 v2, 26, v2
	v_add_u32_e32 v2, v1, v2
	v_lshlrev_b32_e32 v3, 3, v8
	v_ashrrev_i32_e32 v9, 6, v2
	v_and_b32_e32 v3, -16, v3
	v_add_u32_e32 v3, v9, v3
	v_and_b32_e32 v4, 3, v9
	s_mov_b32 s3, 0x1ffffe0
	v_lshrrev_b32_e32 v5, 2, v3
	v_lshlrev_b32_e32 v6, 1, v3
	v_and_b32_e32 v2, 0xc0, v2
	v_and_or_b32 v4, v3, s3, v4
	v_and_b32_e32 v5, 4, v5
	v_and_b32_e32 v6, 24, v6
	v_sub_u32_e32 v1, v1, v2
	v_mov_b32_e32 v2, 1
	v_or3_b32 v4, v4, v5, v6
	v_lshlrev_b32_e32 v5, 5, v8
	v_ashrrev_i16_sdwa v1, v2, sext(v1) dst_sel:DWORD dst_unused:UNUSED_PAD src0_sel:DWORD src1_sel:BYTE_0
	s_movk_i32 s5, 0x180
	v_and_b32_e32 v5, 32, v5
	v_bfe_i32 v11, v1, 0, 16
	v_mul_lo_u32 v4, v4, s5
	v_add_u32_e32 v1, v5, v11
	v_lshlrev_b32_e32 v3, 12, v3
	v_add_lshl_u32 v128, v4, v1, 1
	v_lshl_add_u32 v130, v1, 1, v3
	v_bfe_i32 v1, v10, 27, 1
	v_lshrrev_b32_e32 v1, 22, v1
	v_add_u32_e32 v1, v0, v1
	v_and_b32_e32 v1, 0xfffffc00, v1
	v_sub_u32_e32 v0, v0, v1
	v_lshrrev_b32_e32 v1, 4, v0
	v_ashrrev_i32_e32 v3, 31, v10
	v_bitop3_b32 v0, v1, v0, 32 bitop3:0x6c
	v_lshrrev_b32_e32 v3, 26, v3
	v_ashrrev_i32_e32 v1, 31, v0
	v_add_u32_e32 v3, v10, v3
	v_lshrrev_b32_e32 v1, 26, v1
	v_ashrrev_i32_e32 v13, 6, v3
	v_add_u32_e32 v1, v0, v1
	v_lshlrev_b32_e32 v3, 3, v13
	v_ashrrev_i32_e32 v12, 6, v1
	v_and_b32_e32 v3, -16, v3
	v_add_u32_e32 v3, v12, v3
	v_and_b32_e32 v4, 3, v12
	v_lshrrev_b32_e32 v5, 2, v3
	v_lshlrev_b32_e32 v6, 1, v3
	v_and_or_b32 v4, v3, s3, v4
	v_and_b32_e32 v5, 4, v5
	v_and_b32_e32 v6, 24, v6
	v_or3_b32 v4, v4, v5, v6
	s_ashr_i32 s3, s69, 31
	v_mul_lo_u32 v4, v4, s5
	s_lshr_b32 s5, s3, 29
	s_add_i32 s5, s69, s5
	s_ashr_i32 s1, s0, 6
	s_ashr_i32 s8, s5, 3
	s_and_b32 s5, s5, -8
	s_ashr_i32 s4, s0, 8
	s_lshl_b32 s2, s1, 10
	s_sub_i32 s5, s69, s5
	s_cmp_lt_i32 s5, 0
	s_cselect_b32 s9, 57, 56
	s_mul_i32 s5, s5, s9
	s_add_i32 s5, s5, s8
	s_mul_hi_i32 s8, s5, 0x92492493
	s_add_i32 s8, s8, s5
	s_lshr_b32 s9, s8, 31
	s_ashr_i32 s8, s8, 5
	s_add_i32 s8, s8, s9
	s_lshl_b32 s9, s8, 3
	s_mul_i32 s8, s8, 56
	s_sub_i32 s8, s5, s8
	s_bfe_i32 s5, s8, 0x80000
	s_bfe_u32 s5, s5, 0x3000c
	s_add_i32 s10, s8, s5
	s_bfe_i32 s5, s10, 0x80000
	s_and_b32 s10, s10, 0xf8
	s_sub_i32 s8, s8, s10
	s_sext_i32_i8 s8, s8
	v_and_b32_e32 v1, 0xc0, v1
	s_sext_i32_i16 s14, s5
	s_add_i32 s20, s9, s8
	v_sub_u32_e32 v0, v0, v1
	s_ashr_i32 s21, s20, 31
	s_ashr_i32 s8, s14, 3
	v_lshlrev_b32_e32 v5, 5, v13
	v_ashrrev_i16_sdwa v0, v2, sext(v0) dst_sel:DWORD dst_unused:UNUSED_PAD src0_sel:DWORD src1_sel:BYTE_0
	s_lshr_b32 s5, s14, 3
	s_lshl_b64 s[10:11], s[20:21], 20
	s_mul_hi_i32 s9, s8, 0x30000
	s_mul_i32 s8, s8, 0x30000
	v_and_b32_e32 v5, 32, v5
	v_bfe_i32 v14, v0, 0, 16
	s_cmp_gt_u32 s5, 2
	s_cselect_b32 s99, 0x200, 0
	s_add_u32 s28, s6, s8
	v_add_u32_e32 v0, v5, v14
	s_addc_u32 s29, s7, s9
	s_add_u32 s28, s28, s99
	s_addc_u32 s29, s29, 0
	s_add_i32 s8, s2, 0
	v_add_lshl_u32 v132, v4, v0, 1
	s_add_i32 m0, s8, 0x10000
	v_lshlrev_b32_e32 v1, 12, v3
	global_load_lds_dwordx4 v132, s[28:29]
	s_add_i32 m0, s8, 0x12000
	s_add_u32 s14, s28, 0x18000
	global_load_lds_dwordx4 v128, s[28:29]
	s_addc_u32 s15, s29, 0
	s_add_i32 m0, s8, 0x14000
	v_lshl_add_u32 v134, v0, 1, v1
	global_load_lds_dwordx4 v132, s[14:15]
	s_add_i32 m0, s8, 0x16000
	s_add_u32 s30, s46, s10
	s_addc_u32 s31, s47, s11
	s_add_u32 s30, s30, s99
	s_addc_u32 s31, s31, 0
	s_add_i32 s9, s8, 0x2000
	global_load_lds_dwordx4 v128, s[14:15]
	s_mov_b32 m0, s8
	s_add_u32 s14, s30, 0x80000
	global_load_lds_dwordx4 v134, s[30:31]
	s_mov_b32 m0, s9
	s_addc_u32 s15, s31, 0
	s_add_i32 s10, s8, 0x4000
	global_load_lds_dwordx4 v130, s[30:31]
	s_mov_b32 m0, s10
	s_add_i32 s11, s8, 0x6000
	global_load_lds_dwordx4 v134, s[14:15]
	s_mov_b32 m0, s11
	v_mov_b32_e32 v133, 0
	global_load_lds_dwordx4 v130, s[14:15]
	v_mov_b32_e32 v129, v133
	v_mov_b32_e32 v135, v133
	v_mov_b32_e32 v131, v133
	s_cmp_eq_u32 s4, 1
	s_mov_b32 s21, 0
	v_lshl_add_u64 v[6:7], s[28:29], 0, v[132:133]
	v_lshl_add_u64 v[4:5], s[28:29], 0, v[128:129]
	v_lshl_add_u64 v[0:1], s[30:31], 0, v[134:135]
	s_cselect_b64 s[14:15], -1, 0
	s_cmp_lg_u32 s4, 1
	v_lshl_add_u64 v[2:3], s[30:31], 0, v[130:131]
	s_cbranch_scc1 .LBB0_295
	s_barrier

; __device__ __forceinline__ void phase4a(const Args& a, int gw, int NGW, int lane_) {
;     int lane = lane_; asm volatile("" : "+v"(lane));
;     const bf16_t* PROJ = (const bf16_t*)(a.ws + WS_PROJ); const bf16_t* RAW = (const bf16_t*)(a.ws + WS_QKVRAW);
;     bf16_t* Q = (bf16_t*)(a.ws + WS_XN); bf16_t* K = (bf16_t*)(a.ws + WS_K);
;     const float gq0 = a.g_q[lane], gq1 = a.g_q[lane + 64], gq2 = a.g_q[lane + 128];
;     const float gk0 = a.g_k[lane], gk1 = a.g_k[lane + 64], gk2 = a.g_k[lane + 128];
;     const int fi = lane & 31; const float inv_freq = 1.0f / powf(10000.0f, (float)(2 * fi) / 64.0f);
;     const float qscale = 0.07216878364870322f * 1.4426950408889634f;
;     const float sgn = (lane < 32) ? -1.f : 1.f;
;     TokIn cur, nxt; int m = gw;
;     if (m < T) p4_load(cur, PROJ, RAW, a.pos, m, lane);
.Lpf_skip_2:
	s_add_u32 s0, s82, 0xd000000
	s_addc_u32 s1, s83, 0
	v_writelane_b32 v255, s0, 32
	s_waitcnt lgkmcnt(0)
	v_mov_b32_e32 v0, v224
	s_andn2_b64 vcc, exec, s[12:13]
	v_writelane_b32 v255, s1, 33
	s_barrier
	s_cbranch_vccnz .LBB0_387
	v_ashrrev_i32_e32 v1, 31, v0
	v_readlane_b32 s0, v255, 16
	v_lshlrev_b64 v[2:3], 2, v[0:1]
	v_readlane_b32 s2, v255, 18
	v_readlane_b32 s3, v255, 19
	v_readlane_b32 s4, v255, 20
	v_readlane_b32 s5, v255, 21
	v_lshl_add_u64 v[4:5], s[2:3], 0, v[2:3]
	s_mov_b32 s0, 0x3f2aaaab
	v_lshl_add_u64 v[6:7], s[4:5], 0, v[2:3]
	v_lshlrev_b32_e32 v2, 1, v0
	v_and_b32_e32 v3, 62, v2
	v_cvt_f32_ubyte0_e32 v3, v3
	v_mul_f32_e32 v32, 0x3c800000, v3
	v_mov_b32_e32 v3, 0x461c4000
	v_cmp_eq_f32_e32 vcc, 0, v32
	v_readlane_b32 s1, v255, 17
	s_mov_b32 s1, 0x42b17218
	v_cndmask_b32_e64 v3, v3, 1.0, vcc
	v_frexp_mant_f32_e32 v8, v3
	v_cmp_gt_f32_e32 vcc, s0, v8
	s_mov_b32 s0, 0x3f317218
	s_mov_b32 s2, 0x3fb8aa3b
	v_cndmask_b32_e64 v9, 1.0, 2.0, vcc
	v_mul_f32_e32 v8, v8, v9
	v_add_f32_e32 v11, 1.0, v8
	v_rcp_f32_e32 v16, v11
	v_add_f32_e32 v9, -1.0, v11
	v_sub_f32_e32 v13, v8, v9
	v_add_f32_e32 v9, -1.0, v8
	v_mul_f32_e32 v17, v9, v16
	v_mul_f32_e32 v10, v11, v17
	v_fma_f32 v12, v17, v11, -v10
	v_fmac_f32_e32 v12, v17, v13
	v_add_f32_e32 v8, v10, v12
	v_sub_f32_e32 v11, v9, v8
	v_pk_add_f32 v[14:15], v[8:9], v[10:11] neg_lo:[0,1] neg_hi:[0,1]
	v_mov_b32_e32 v13, v8
	v_pk_add_f32 v[8:9], v[14:15], v[12:13] neg_lo:[0,1] neg_hi:[0,1]
	v_mov_b32_e32 v12, 0x3e91f4c4
	v_add_f32_e32 v8, v8, v9
	v_add_f32_e32 v8, v11, v8
	v_mul_f32_e32 v9, v16, v8
	v_add_f32_e32 v8, v17, v9
	v_sub_f32_e32 v10, v8, v17
	v_sub_f32_e32 v18, v9, v10
	v_mul_f32_e32 v9, v8, v8
	v_fma_f32 v11, v8, v8, -v9
	v_add_f32_e32 v10, v18, v18
	v_fmac_f32_e32 v11, v8, v10
	v_add_f32_e32 v10, v9, v11
	v_fmac_f32_e32 v12, 0x3e76c4e1, v10
	v_fmaak_f32 v12, v10, v12, 0x3ecccdef
	v_sub_f32_e32 v9, v10, v9
	v_sub_f32_e32 v19, v11, v9
	v_mul_f32_e32 v9, v10, v12
	v_fma_f32 v11, v10, v12, -v9
	v_fmac_f32_e32 v11, v19, v12
	v_add_f32_e32 v12, v9, v11
	v_add_f32_e32 v13, 0x3f2aaaaa, v12
	v_sub_f32_e32 v9, v12, v9
	v_sub_f32_e32 v9, v11, v9
	v_add_f32_e32 v11, 0xbf2aaaaa, v13
	v_add_f32_e32 v9, 0x31739010, v9
	v_sub_f32_e32 v11, v12, v11
	v_pk_mul_f32 v[14:15], v[8:9], v[10:11]
	v_pk_add_f32 v[16:17], v[8:9], v[10:11]
	v_fma_f32 v12, v10, v8, -v14
	v_fmac_f32_e32 v12, v10, v18
	v_mov_b32_e32 v15, v17
	v_fmac_f32_e32 v12, v19, v8
	v_pk_add_f32 v[10:11], v[14:15], v[12:13]
	s_mov_b32 s4, 0x7f800000
	v_sub_f32_e32 v9, v10, v14
	v_sub_f32_e32 v9, v12, v9
	v_sub_f32_e32 v12, v13, v11
	v_add_f32_e32 v15, v17, v12
	v_cvt_f64_f32_e32 v[16:17], v3
	v_frexp_exp_i32_f64_e32 v3, v[16:17]
	v_subbrev_co_u32_e32 v3, vcc, 0, v3, vcc
	v_cvt_f32_i32_e32 v3, v3
	v_pk_mul_f32 v[12:13], v[10:11], v[10:11] op_sel:[0,1] op_sel_hi:[1,0]
	v_ldexp_f32 v17, v8, 1
	v_fma_f32 v14, v10, v11, -v12
	v_fmac_f32_e32 v14, v10, v15
	v_mul_f32_e32 v10, 0x3f317218, v3
	v_fmac_f32_e32 v14, v9, v11
	v_fma_f32 v9, v3, s0, -v10
	v_fmamk_f32 v16, v3, 0xb102e308, v9
	v_add_f32_e32 v11, v12, v14
	v_pk_add_f32 v[8:9], v[10:11], v[16:17]
	v_ldexp_f32 v3, v18, 1
	v_mov_b32_e32 v18, v11
	v_mov_b32_e32 v19, v9
	v_mov_b32_e32 v13, v17
	v_pk_add_f32 v[12:13], v[18:19], v[12:13] neg_lo:[0,1] neg_hi:[0,1]
	v_mov_b32_e32 v15, v11
	v_pk_add_f32 v[12:13], v[14:15], v[12:13] neg_lo:[0,1] neg_hi:[0,1]
	v_mov_b32_e32 v17, v8
	v_add_f32_e32 v3, v3, v12
	v_add_f32_e32 v11, v3, v13
	v_pk_add_f32 v[12:13], v[8:9], v[10:11] neg_lo:[0,1] neg_hi:[0,1]
	v_pk_add_f32 v[14:15], v[8:9], v[10:11]
	v_mov_b32_e32 v10, v11
	v_mov_b32_e32 v13, v15
	v_pk_add_f32 v[18:19], v[16:17], v[12:13] neg_lo:[0,1] neg_hi:[0,1]
	v_pk_add_f32 v[12:13], v[16:17], v[12:13]
	v_mov_b32_e32 v11, v8
	v_pk_add_f32 v[16:17], v[12:13], v[8:9] op_sel:[1,0] op_sel_hi:[0,1] neg_lo:[0,1] neg_hi:[0,1]
	v_pk_add_f32 v[20:21], v[14:15], v[16:17] op_sel_hi:[1,0] neg_lo:[0,1] neg_hi:[0,1]
	v_mov_b32_e32 v14, v15
	v_mov_b32_e32 v15, v13
	v_pk_mov_b32 v[16:17], v[8:9], v[16:17] op_sel:[1,0]
	v_mov_b32_e32 v20, v18
	v_pk_add_f32 v[14:15], v[14:15], v[16:17] neg_lo:[0,1] neg_hi:[0,1]
	v_mov_b32_e32 v19, v13
	v_pk_add_f32 v[8:9], v[10:11], v[14:15] neg_lo:[0,1] neg_hi:[0,1]
	s_movk_i32 s0, 0x204
	v_pk_add_f32 v[10:11], v[20:21], v[8:9]
	s_ashr_i32 s85, s84, 31
	v_pk_add_f32 v[14:15], v[10:11], v[10:11] op_sel:[0,1] op_sel_hi:[1,0]
	global_load_dword v26, v[6:7], off
	global_load_dword v27, v[6:7], off offset:256
	global_load_dword v28, v[6:7], off offset:512
	v_pk_add_f32 v[12:13], v[12:13], v[14:15] op_sel:[1,0] op_sel_hi:[0,1]
	v_mov_b32_e32 v11, v12
	v_pk_add_f32 v[16:17], v[10:11], v[18:19] neg_lo:[0,1] neg_hi:[0,1]
	v_mov_b32_e32 v9, v14
	v_sub_f32_e32 v3, v10, v16
	v_pk_add_f32 v[8:9], v[8:9], v[16:17] neg_lo:[0,1] neg_hi:[0,1]
	v_sub_f32_e32 v3, v18, v3
	v_add_f32_e32 v3, v8, v3
	v_add_f32_e32 v3, v3, v9
	v_add_f32_e32 v8, v12, v3
	v_sub_f32_e32 v9, v8, v12
	v_sub_f32_e32 v3, v3, v9
	v_mul_f32_e32 v9, v32, v8
	v_fma_f32 v8, v32, v8, -v9
	v_fmac_f32_e32 v8, v32, v3
	v_add_f32_e32 v3, v9, v8
	v_cmp_class_f32_e64 vcc, v9, s0
	v_sub_f32_e32 v10, v3, v9
	v_sub_f32_e32 v8, v8, v10
	v_cndmask_b32_e32 v3, v3, v9, vcc
	v_mov_b32_e32 v9, 0x37000000
	v_cmp_eq_f32_e32 vcc, s1, v3
	v_readlane_b32 s8, v255, 24
	v_readlane_b32 s9, v255, 25
	v_cndmask_b32_e32 v9, 0, v9, vcc
	v_sub_f32_e32 v10, v3, v9
	v_mul_f32_e32 v11, 0x3fb8aa3b, v10
	v_fma_f32 v12, v10, s2, -v11
	v_rndne_f32_e32 v13, v11
	v_fmamk_f32 v12, v10, 0x32a5705f, v12
; __device__ __forceinline__ unsigned pk2(float a, float b) { f32x2_t v = {a, b}; bf16x2v_t r = __builtin_convertvector(v, bf16x2v_t); return __builtin_bit_cast(unsigned, r); }
; __device__ __forceinline__ void p4_load(TokIn& t, const bf16_t* PROJ, const bf16_t* RAW, const int* pos, int m, int lane) {
;     const bf16_t* pr = PROJ + (size_t)m * PP; const bf16_t* rr = RAW + (size_t)m * UPN;
; #pragma unroll
;     for (int h = 0; h < NH; ++h) {
; #pragma unroll
;         for (int i = 0; i < 3; ++i) t.q[h][i] = rr[h * QKD + lane + 64 * i];
; #pragma unroll
;         for (int i = 0; i < 2; ++i) t.k[h][i] = rr[768 + h * 256 + lane + 64 * i];
;     }
;     t.kpe = pr[C_KPE + lane]; t.cq = *(const u32x2*)(pr + C_CQ + 4 * lane); t.ckv = *(const unsigned*)(pr + C_CKV + 2 * lane); t.pos = pos[m];
; }
; __device__ __forceinline__ unsigned short bf16r(float v) { return (unsigned short)(pk2(v, 0.f) & 0xffffu); }
; __device__ __forceinline__ void phase4a(const Args& a, int gw, int NGW, int lane_) {
;     int lane = lane_; asm volatile("" : "+v"(lane));
;     const bf16_t* PROJ = (const bf16_t*)(a.ws + WS_PROJ); const bf16_t* RAW = (const bf16_t*)(a.ws + WS_QKVRAW);
;     bf16_t* Q = (bf16_t*)(a.ws + WS_XN); bf16_t* K = (bf16_t*)(a.ws + WS_K);
;     const float gq0 = a.g_q[lane], gq1 = a.g_q[lane + 64], gq2 = a.g_q[lane + 128];
;     const float gk0 = a.g_k[lane], gk1 = a.g_k[lane + 64], gk2 = a.g_k[lane + 128];
;     const int fi = lane & 31; const float inv_freq = 1.0f / powf(10000.0f, (float)(2 * fi) / 64.0f);
;     const float qscale = 0.07216878364870322f * 1.4426950408889634f;
;     const float sgn = (lane < 32) ? -1.f : 1.f;
;     TokIn cur, nxt; int m = gw;
;     if (m < T) p4_load(cur, PROJ, RAW, a.pos, m, lane);
	v_sub_f32_e32 v11, v11, v13
	v_add_f32_e32 v11, v11, v12
	v_exp_f32_e32 v11, v11
	v_cvt_i32_f32_e32 v12, v13
	v_cmp_neq_f32_e64 vcc, |v3|, s4
	s_mov_b32 s2, 0xc2ce8ed0
	v_readlane_b32 s10, v255, 26
	v_cndmask_b32_e32 v3, 0, v8, vcc
	v_ldexp_f32 v8, v11, v12
	v_cmp_ngt_f32_e32 vcc, s2, v10
	v_add_f32_e32 v3, v9, v3
	v_mov_b32_e32 v9, 0x7f800000
	v_cndmask_b32_e32 v8, 0, v8, vcc
	v_cmp_nlt_f32_e32 vcc, s1, v10
	v_lshlrev_b64 v[12:13], 1, v[0:1]
	v_readlane_b32 s11, v255, 27
	v_cndmask_b32_e32 v8, v9, v8, vcc
	v_fma_f32 v3, v8, v3, v8
	v_cmp_class_f32_e64 vcc, v8, s0
	v_readlane_b32 s12, v255, 28
	v_readlane_b32 s13, v255, 29
	v_cndmask_b32_e32 v14, v3, v8, vcc
	v_and_b32_e32 v15, 0x7fffffff, v14
	v_div_scale_f32 v33, s[0:1], v15, v15, 1.0
	s_mul_i32 s0, s84, 0xe00
	s_mul_hi_i32 s1, s84, 0xe00
	s_add_u32 s0, s64, s0
	s_addc_u32 s1, s65, s1
	v_lshl_add_u64 v[6:7], s[0:1], 0, v[12:13]
	s_lshl_b64 s[0:1], s[84:85], 12
	s_add_u32 s0, s46, s0
	s_addc_u32 s1, s47, s1
	global_load_ushort v23, v[6:7], off offset:1536 nt
	global_load_ushort v22, v[6:7], off offset:1664 nt
	global_load_ushort v21, v[6:7], off offset:2048 nt
	global_load_ushort v20, v[6:7], off offset:2176 nt
	global_load_ushort v19, v[6:7], off offset:1024 nt
	global_load_ushort v18, v[6:7], off offset:1152 nt
	global_load_ushort v40, v[6:7], off offset:1280 nt
	global_load_ushort v41, v[6:7], off offset:1408 nt
	global_load_dword v29, v[4:5], off
	global_load_dword v30, v[4:5], off offset:256
	global_load_dword v31, v[4:5], off offset:512
	global_load_ushort v78, v[6:7], off nt
	global_load_ushort v77, v[6:7], off offset:128 nt
	global_load_ushort v76, v[6:7], off offset:256 nt
	global_load_ushort v75, v[6:7], off offset:384 nt
	global_load_ushort v74, v[6:7], off offset:512 nt
	global_load_ushort v73, v[6:7], off offset:640 nt
	global_load_ushort v71, v[6:7], off offset:768 nt
	global_load_ushort v70, v[6:7], off offset:896 nt
	v_lshl_add_u64 v[4:5], s[0:1], 0, v[12:13]
	v_ashrrev_i32_e32 v3, 31, v2
	v_readlane_b32 s14, v255, 30
	v_readlane_b32 s15, v255, 31
	v_mad_i64_i32 v[8:9], s[2:3], v0, 6, v[4:5]
	v_lshl_add_u64 v[10:11], v[2:3], 1, s[0:1]
	global_load_ushort v82, v[6:7], off offset:2560 nt
	global_load_ushort v72, v[6:7], off offset:2688 nt
	global_load_ushort v25, v[6:7], off offset:3072 nt
	global_load_ushort v24, v[6:7], off offset:3200 nt
	global_load_ushort v79, v[4:5], off offset:768 nt
	global_load_dwordx2 v[16:17], v[8:9], off
	global_load_dword v80, v[10:11], off offset:512
	v_readlane_b32 s8, v255, 0
	s_lshl_b64 s[0:1], s[84:85], 2
	v_readlane_b32 s12, v255, 4
	v_readlane_b32 s13, v255, 5
	s_add_u32 s0, s12, s0
	s_addc_u32 s1, s13, s1
	v_mov_b32_e32 v5, 0
	global_load_dword v4, v5, s[0:1]
	v_rcp_f32_e32 v34, v33
	v_readlane_b32 s9, v255, 1
	v_readlane_b32 s10, v255, 2
	v_readlane_b32 s11, v255, 3
	v_fma_f32 v6, -v33, v34, 1.0
	v_fmac_f32_e32 v34, v6, v34
	v_div_scale_f32 v6, vcc, 1.0, v15, 1.0
	v_mul_f32_e32 v7, v6, v34
	v_fma_f32 v8, -v33, v7, v6
	v_fmac_f32_e32 v7, v8, v34
	v_fma_f32 v6, -v33, v7, v6
	v_mbcnt_lo_u32_b32 v8, -1, 0
	v_div_fmas_f32 v6, v6, v34, v7
	v_mbcnt_hi_u32_b32 v8, -1, v8
	v_div_fixup_f32 v6, v6, |v14|, 1.0
	v_cmp_neq_f32_e32 vcc, s4, v32
	v_and_b32_e32 v9, 64, v8
	v_add_u32_e32 v9, 64, v9
	v_cndmask_b32_e32 v32, 0, v6, vcc
	v_cmp_gt_i32_e32 vcc, 32, v0
	v_xor_b32_e32 v10, 32, v8
	v_mad_i64_i32 v[6:7], s[0:1], v0, 6, 0
	v_cndmask_b32_e64 v33, 1.0, -1.0, vcc
	v_cmp_lt_i32_e32 vcc, v10, v9
	v_readlane_b32 s0, v255, 32
	v_readlane_b32 s14, v255, 6
	v_cndmask_b32_e32 v10, v8, v10, vcc
	v_lshlrev_b32_e32 v34, 2, v10
	v_xor_b32_e32 v10, 1, v8
	v_cmp_lt_i32_e32 vcc, v10, v9
	v_readlane_b32 s15, v255, 7
	v_readlane_b32 s16, v255, 8
	v_cndmask_b32_e32 v10, v8, v10, vcc
	v_lshlrev_b32_e32 v35, 2, v10
	v_xor_b32_e32 v10, 2, v8
	v_cmp_lt_i32_e32 vcc, v10, v9
	v_readlane_b32 s17, v255, 9
	s_mov_b32 s2, 0x5040100
	v_cndmask_b32_e32 v10, v8, v10, vcc
	v_lshlrev_b32_e32 v36, 2, v10
	v_xor_b32_e32 v10, 4, v8
	v_cmp_lt_i32_e32 vcc, v10, v9
	v_readlane_b32 s1, v255, 33
	s_brev_b32 s12, 60
	v_cndmask_b32_e32 v10, v8, v10, vcc
	v_lshlrev_b32_e32 v37, 2, v10
	v_xor_b32_e32 v10, 8, v8
	v_cmp_lt_i32_e32 vcc, v10, v9
	s_brev_b32 s3, 18
	s_waitcnt vmcnt(19)
	v_perm_b32 v89, v40, v41, s2
	v_cndmask_b32_e32 v10, v8, v10, vcc
	v_lshlrev_b32_e32 v38, 2, v10
	v_xor_b32_e32 v10, 16, v8
	v_cmp_lt_i32_e32 vcc, v10, v9
	s_mov_b32 s8, 0x800000
	s_mov_b32 s9, 0xfe5163ab
	v_cndmask_b32_e32 v8, v8, v10, vcc
	v_lshlrev_b32_e32 v39, 2, v8
	v_lshl_add_u64 v[8:9], s[64:65], 0, v[12:13]
	v_lshl_add_u64 v[10:11], s[94:95], 0, v[12:13]
	v_lshl_add_u64 v[12:13], s[0:1], 0, v[12:13]
	s_mov_b32 s10, 0x3c439041
	s_mov_b32 s11, 0xdb629599
	s_mov_b32 s15, 0xf534ddc0
	s_mov_b32 s17, 0xfc2757d1
	s_mov_b32 s24, 0x4e441529
	s_mov_b32 s25, 0xa2f9836e
	s_mov_b32 s26, 0x3fc90fda
	s_mov_b32 s27, 0x3f22f983
	s_mov_b32 s28, 0xbfc90fda
	s_mov_b32 s13, 0x3b800000
	v_mov_b32_e32 v40, 0x358637bd
	s_mov_b32 s14, 0x358637bd
	v_mov_b32_e32 v41, 0x3c0881c4
	v_mov_b32_e32 v42, 0xbab64f3b
	s_brev_b32 s29, 1
	s_movk_i32 s30, 0x1f8
	s_mov_b32 s16, 0x3baaaaab
	v_mov_b32_e32 v43, 0xe00
	v_not_b32_e32 v44, 63
	v_not_b32_e32 v45, 31
	v_mov_b32_e32 v46, 0x7fc00000
	v_mov_b32_e32 v47, 0x180
	s_mov_b32 s31, s84
	v_readlane_b32 s6, v255, 22
	v_readlane_b32 s7, v255, 23
	v_readlane_b32 s18, v255, 10
	v_readlane_b32 s19, v255, 11
	v_readlane_b32 s20, v255, 12
	v_readlane_b32 s21, v255, 13
	v_readlane_b32 s22, v255, 14
	v_readlane_b32 s23, v255, 15
	s_branch .LBB0_381

; #define LAS __attribute__((address_space(3)))
; __device__ __forceinline__ void attn_unit(LAS unsigned char* lds, const bf16_t* Qg, const bf16_t* Kg, const bf16_t* Vtg, bf16_t* Og, int bh, int qb, int tid_, int wave, int lane_) {
;     int tid = tid_; asm volatile("" : "+v"(tid));
;     const int lane = tid & 63;
;     const int rg = wave & 3, kh = wave >> 2, r = lane & 31, hi = lane >> 5;
;     const int b = bh >> 2, h = bh & 3;
;     const int nt = 2 * (qb + 1);
;     const float NEG = -1e30f;
;     bf16x8 qf[12];
;     { const bf16_t* qp = Qg + ((size_t)bh * SEQ + 128 * qb + 32 * rg + r) * QKD + 8 * hi;
; #pragma unroll
;       for (int kk = 0; kk < 12; ++kk) qf[kk] = *(const bf16x8*)(qp + 16 * kk); }
;     const unsigned char* kg = (const unsigned char*)(Kg + (size_t)bh * SEQ * QKD);
;     const unsigned char* vg = (const unsigned char*)(Vtg + (size_t)bh * VD * SEQ);
;     unsigned kgo[3], vgo[2];
; #pragma unroll
;     for (int i = 0; i < 3; ++i) { const int a = (wave * 3 + i) * 1024 + lane * 16, row = a / 384, cp = (a % 384) >> 4, cl = (cp & ~7) | ((cp ^ (row >> 1)) & 7); kgo[i] = (unsigned)(row * 384 + cl * 16); }
; #pragma unroll
;     for (int i = 0; i < 2; ++i) { const int a = (wave * 2 + i) * 1024 + lane * 16, row = a >> 7, cp = (a & 127) >> 4, cl = (cp ^ (row >> 1)) & 7; vgo[i] = (unsigned)(row * (SEQ * 2) + cl * 16); }
;     const int sw = (r >> 1) & 7;
;     unsigned kro[4], vro[2];
; #pragma unroll
;     for (int q = 0; q < 4; ++q) kro[q] = (unsigned)((32 * kh + r) * 384 + (((2 * q + hi) ^ sw) * 16));
; #pragma unroll
;     for (int s = 0; s < 2; ++s) vro[s] = (unsigned)(VRING + r * 128 + (((4 * kh + 2 * s + hi) ^ sw) * 16));
; __global__ void __launch_bounds__(NTHREADS, 2) fwd_megakernel(Args a) {
;     ...
;     xcd_barrier(bar);
;     { const bf16_t* Qg = XN; const bf16_t* Kg = (const bf16_t*)(ws + WS_K); const bf16_t* Vtg = (const bf16_t*)(ws + WS_VT); bf16_t* Og = RAW;
;       for (int c = blockIdx.x; c < 256; c += G) { const int bh = c & 7, pi = c >> 3;
;           attn_unit(lds, Qg, Kg, Vtg, Og, bh, 63 - pi, tid, wave, lane);
.LBB0_472:
	v_writelane_b32 v255, s64, 34
	s_nop 1
	v_writelane_b32 v255, s65, 35
	v_writelane_b32 v255, s94, 36
	s_nop 1
	v_writelane_b32 v255, s95, 37
	v_writelane_b32 v255, s90, 38
	v_writelane_b32 v255, s86, 39
	s_nop 1
	v_writelane_b32 v255, s87, 40
	v_writelane_b32 v255, s84, 41
	s_nop 1
	v_writelane_b32 v255, s85, 42
	v_writelane_b32 v255, s75, 43
	v_writelane_b32 v255, s74, 44
	v_writelane_b32 v255, s72, 45
	s_nop 1
	v_writelane_b32 v255, s73, 46
	v_writelane_b32 v255, s70, 47
	s_nop 1
	v_writelane_b32 v255, s71, 48
	v_writelane_b32 v255, s69, 49
	s_or_b64 exec, exec, s[0:1]
	v_readfirstlane_b32 s98, v254
	s_lshr_b32 s98, s98, 6
	s_cmp_lg_u32 s98, 1
	s_cbranch_scc1 .Lpf_skip_3
	s_getpc_b64 s[100:101]
	v_and_b32_e32 v110, 63, v254
	v_lshlrev_b32_e32 v110, 7, v110
	global_load_dword v111, v110, s[100:101]
	s_add_u32 s100, s100, 0x2000
	s_addc_u32 s101, s101, 0
	global_load_dword v111, v110, s[100:101]
	s_add_u32 s100, s100, 0x2000
	s_addc_u32 s101, s101, 0
	global_load_dword v111, v110, s[100:101]
	s_waitcnt vmcnt(0)
.Lpf_skip_3:
	v_writelane_b32 v255, s96, 50
	s_and_b64 vcc, exec, s[96:97]
	s_waitcnt lgkmcnt(0)
	v_writelane_b32 v255, s97, 51
	s_barrier
	s_cbranch_vccnz .LBB0_499
	s_add_u32 s0, s82, 0xe800000
	v_writelane_b32 v255, s0, 52
	s_addc_u32 s0, s83, 0
	v_writelane_b32 v255, s0, 53
	s_bfe_u32 s0, s92, 0x20006
	v_readlane_b32 s2, v255, 38
	s_lshl_b32 s68, s2, 11
	s_lshl_b32 s97, s0, 5
	s_lshr_b32 s1, s92, 8
	s_mul_i32 s59, s2, 0xc00
	s_add_i32 s10, s68, 0
	s_mulk_i32 s0, 0x4200
	s_add_i32 s60, s59, 0x400
	s_add_i32 s67, s59, 0x800
	s_lshl_b32 s69, s1, 5
	s_and_b32 s70, s2, 0x3fffffc
	s_add_i32 s71, s59, 0
	s_add_i32 s96, s10, 0x12000
	s_add_i32 s43, s10, 0x12400
	s_add_i32 s33, s10, 0x16000
	s_add_i32 s10, s10, 0x16400
	s_add_i32 s11, s0, 0
	s_cmp_eq_u32 s1, 1
	s_cselect_b64 s[64:65], -1, 0
	s_cmpk_lt_u32 s92, 0x100
	s_cselect_b64 s[76:77], -1, 0
	s_sub_i32 s0, s69, s97
	s_addk_i32 s0, 0xe080
	v_writelane_b32 v255, s0, 54
	s_sub_i32 s0, 0, s97
	v_writelane_b32 v255, s0, 55
	s_mov_b32 s49, 0
	v_readlane_b32 s0, v255, 36
	v_readlane_b32 s1, v255, 37
	v_mov_b32_e32 v177, 0
	s_movk_i32 s61, 0x180
	v_mov_b64_e32 v[178:179], s[0:1]
	v_mov_b32_e32 v195, 0x180
	s_mov_b32 s42, 0x2aaaaaab
	s_movk_i32 s86, 0x70
	s_mov_b32 s62, 0xfffdc000
	s_add_i32 s91, s71, 0x400
	s_add_i32 s74, s71, 0x800
	s_add_i32 s75, s71, 0x6000
	s_add_i32 s90, s71, 0x6400
	s_add_i32 s2, s71, 0x6800
	s_add_i32 s85, s71, 0xc000
	s_add_i32 s87, s71, 0xc400
	s_add_i32 s3, s71, 0xc800
	s_mov_b64 s[78:79], 0x80
	v_mov_b32_e32 v196, 0xff800000
	v_readlane_b32 s72, v255, 49
	s_branch .LBB0_475

; __device__ __forceinline__ void unpack8(const u32x4 v, float (&f)[8]) { f[0] = bflo(v.x); f[1] = bfhi(v.x); f[2] = bflo(v.y); f[3] = bfhi(v.y); f[4] = bflo(v.z); f[5] = bfhi(v.z); f[6] = bflo(v.w); f[7] = bfhi(v.w); }
; __device__ __forceinline__ void phase6(const Args& a, int gw, int NGW, int lane_) {
;     int lane = lane_; asm volatile("" : "+v"(lane));
;     const bf16_t* PROJ = (const bf16_t*)(a.ws + WS_PROJ); const bf16_t* O = (const bf16_t*)(a.ws + WS_QKVRAW); bf16_t* Y = (bf16_t*)(a.ws + WS_XN);
;     const int c0 = 8 * lane;
;     float goa[8], goc[8], w0[8], w1[8], w2[8];
; #pragma unroll
;     for (int e = 0; e < 8; ++e) { goa[e] = a.g_oa[c0 + e]; goc[e] = a.g_oc[c0 + e]; w0[e] = a.conv_w[c0 + e]; w1[e] = a.conv_w[CW + c0 + e]; w2[e] = a.conv_w[2 * CW + c0 + e]; }
;     for (int ch = gw; ch < T / 8; ch += NGW) {
;         const int m0 = ch * 8, s0 = m0 % SEQ;
;         float pm2[8], pm1[8];
;         if (s0 >= 2) { unpack8(*(const u32x4*)(PROJ + (size_t)(m0 - 1) * PP + C_PR + c0), pm1); unpack8(*(const u32x4*)(PROJ + (size_t)(m0 - 2) * PP + C_PR + c0), pm2); }
.Lpf_skip_4:
	v_readlane_b32 s74, v255, 50
	s_cmpk_gt_i32 s26, 0x7ff
	v_readlane_b32 s75, v255, 51
	s_waitcnt lgkmcnt(0)
	s_barrier
	s_cbranch_scc1 .LBB0_561
	v_lshlrev_b32_e32 v40, 3, v224
	v_ashrrev_i32_e32 v41, 31, v40
	v_readlane_b32 s0, v255, 16
	v_lshlrev_b64 v[16:17], 2, v[40:41]
	v_readlane_b32 s1, v255, 17
	v_readlane_b32 s6, v255, 22
	v_readlane_b32 s7, v255, 23
	s_mov_b64 s[0:1], 0x1000
	v_readlane_b32 s8, v255, 24
	v_lshl_add_u64 v[42:43], s[6:7], 0, v[16:17]
	v_lshl_add_u64 v[44:45], v[42:43], 0, s[0:1]
	s_movk_i32 s0, 0x1000
	v_readlane_b32 s9, v255, 25
	v_readlane_b32 s10, v255, 26
	v_readlane_b32 s11, v255, 27
	v_add_co_u32_e32 v46, vcc, s0, v42
	v_lshl_add_u64 v[18:19], s[8:9], 0, v[16:17]
	v_lshl_add_u64 v[20:21], s[10:11], 0, v[16:17]
	v_addc_co_u32_e32 v47, vcc, 0, v43, vcc
	global_load_dwordx4 v[0:3], v[18:19], off offset:16
	global_load_dwordx4 v[4:7], v[18:19], off
	global_load_dwordx4 v[8:11], v[20:21], off offset:16
	global_load_dwordx4 v[12:15], v[20:21], off
	s_nop 0
	global_load_dwordx4 v[16:19], v[46:47], off
	global_load_dwordx4 v[20:23], v[44:45], off offset:16
	global_load_dwordx4 v[24:27], v[42:43], off offset:2064
	global_load_dwordx4 v[28:31], v[42:43], off offset:2048
	global_load_dwordx4 v[32:35], v[42:43], off offset:16
	global_load_dwordx4 v[36:39], v[42:43], off
	v_mbcnt_lo_u32_b32 v42, -1, 0
	v_mbcnt_hi_u32_b32 v42, -1, v42
	v_and_b32_e32 v43, 64, v42
	v_add_u32_e32 v43, 64, v43
	v_xor_b32_e32 v44, 1, v42
	v_cmp_lt_i32_e32 vcc, v44, v43
	v_readlane_b32 s0, v255, 34
	v_lshlrev_b64 v[40:41], 1, v[40:41]
	v_cndmask_b32_e32 v44, v42, v44, vcc
	v_lshlrev_b32_e32 v79, 2, v44
	v_xor_b32_e32 v44, 2, v42
	v_cmp_lt_i32_e32 vcc, v44, v43
	v_readlane_b32 s1, v255, 35
	v_readlane_b32 s2, v255, 18
	v_cndmask_b32_e32 v44, v42, v44, vcc
	v_lshlrev_b32_e32 v106, 2, v44
	v_xor_b32_e32 v44, 4, v42
	v_cmp_lt_i32_e32 vcc, v44, v43
	v_readlane_b32 s3, v255, 19
	v_lshl_add_u64 v[72:73], s[0:1], 0, v[40:41]
	v_cndmask_b32_e32 v44, v42, v44, vcc
	v_lshlrev_b32_e32 v107, 2, v44
	v_xor_b32_e32 v44, 8, v42
	v_cmp_lt_i32_e32 vcc, v44, v43
	s_lshl_b32 s0, s67, 6
	s_lshl_b32 s1, s27, 3
	v_cndmask_b32_e32 v44, v42, v44, vcc
	v_lshlrev_b32_e32 v108, 2, v44
	v_xor_b32_e32 v44, 16, v42
	v_cmp_lt_i32_e32 vcc, v44, v43
	v_lshl_add_u64 v[74:75], s[46:47], 0, v[40:41]
	v_lshl_add_u64 v[76:77], s[72:73], 0, v[40:41]
	v_cndmask_b32_e32 v44, v42, v44, vcc
	v_lshlrev_b32_e32 v109, 2, v44
	v_xor_b32_e32 v44, 32, v42
	v_cmp_lt_i32_e32 vcc, v44, v43
	s_add_i32 s1, s0, s1
	s_lshl_b32 s2, s88, 6
	v_cndmask_b32_e32 v42, v42, v44, vcc
	v_lshlrev_b32_e32 v110, 2, v42
	s_mov_b32 s0, 0x3b000000
	s_mov_b32 s3, 0x800000
	v_mov_b32_e32 v78, 0x358637bd
	v_mov_b32_e32 v80, 0
	v_readlane_b32 s4, v255, 20
	v_readlane_b32 s5, v255, 21
	v_readlane_b32 s12, v255, 28
	v_readlane_b32 s13, v255, 29
	v_readlane_b32 s14, v255, 30
	v_readlane_b32 s15, v255, 31
	s_branch .LBB0_554

;     __host__ __device__ bool next(int i, Unit& u) const {
;         const long L = (long)i * G + c; if (L >= nwg) return false;
;         int wgid = (int)L; { const int q = nwg / NXCD, r = nwg % NXCD, xcd = wgid % NXCD, off = wgid / NXCD; wgid = (xcd < r ? xcd * (q + 1) : r * (q + 1) + (xcd - r) * q) + off; }
;         const int nig = WGM * nN, gid = wgid / nig, fm = gid * WGM, gsz = (nM - fm) < WGM ? (nM - fm) : WGM;
;         u.pm = fm + ((wgid % nig) % gsz); u.pn = (wgid % nig) / gsz; return true;
; __global__ void __launch_bounds__(NTHREADS, 2) fwd_megakernel(Args a) {
;     ...
;     xcd_barrier(bar);
;     { pg8::Gemm g{XN, (const bf16_t*)(ws + WS_WO), T, DM, DM, DM}; pg8::StaticOrder S; S.init(T, DM, G, (int)blockIdx.x);
;       pg8::EpiX1 E{a.x, a.out, (bf16_t*)(ws + WS_X1B), (float*)(ws + WS_ROWSQ), DM};
;       pg8::gemm_phase<pg8::EpiX1, pg8::StaticOrder, true, true>(lds, g, S, E); }
.Lpf_skip_5:
	v_mov_b32_e32 v8, v254
	s_waitcnt lgkmcnt(0)
	s_barrier
	s_and_b64 vcc, exec, s[74:75]
	v_readfirstlane_b32 s4, v8
	s_cbranch_vccnz .LBB0_619
	s_ashr_i32 s0, s67, 31
	s_lshr_b32 s0, s0, 29
	s_add_i32 s2, s67, s0
	s_and_b32 s0, s2, -8
	s_sub_i32 s3, s67, s0
	s_cmp_gt_i32 s3, -1
	s_cbranch_scc0 .LBB0_616
	s_lshl_b32 s5, s3, 5
	s_cbranch_execz .LBB0_617
	s_branch .LBB0_618

;     __host__ __device__ bool next(int i, Unit& u) const {
;         const long L = (long)i * G + c; if (L >= nwg) return false;
;         int wgid = (int)L; { const int q = nwg / NXCD, r = nwg % NXCD, xcd = wgid % NXCD, off = wgid / NXCD; wgid = (xcd < r ? xcd * (q + 1) : r * (q + 1) + (xcd - r) * q) + off; }
;         const int nig = WGM * nN, gid = wgid / nig, fm = gid * WGM, gsz = (nM - fm) < WGM ? (nM - fm) : WGM;
;         u.pm = fm + ((wgid % nig) % gsz); u.pn = (wgid % nig) / gsz; return true;
; __global__ void __launch_bounds__(NTHREADS, 2) fwd_megakernel(Args a) {
;     ...
;     xcd_barrier(bar);
;     { pg8::Gemm g{(const bf16_t*)(ws + WS_X1B), (const bf16_t*)(ws + WS_WPLG), T, DM, DM, DM}; pg8::StaticOrder S; S.init(T, DM, G, (int)blockIdx.x);
;       pg8::EpiGateOut E{(const bf16_t*)(ws + WS_PL), (const bf16_t*)(ws + WS_X1B), a.out, (const float*)(ws + WS_ROWSQ), DM, EPS};
;       pg8::gemm_phase<pg8::EpiGateOut, pg8::StaticOrder, true, true>(lds, g, S, E); }
.LBB0_707:
	s_or_b64 exec, exec, s[0:1]
	v_readfirstlane_b32 s98, v254
	s_lshr_b32 s98, s98, 6
	s_cmp_lg_u32 s98, 1
	s_cbranch_scc1 .Lpf_skip_6
	s_getpc_b64 s[100:101]
	v_and_b32_e32 v110, 63, v254
	v_lshlrev_b32_e32 v110, 7, v110
	global_load_dword v111, v110, s[100:101]
	s_waitcnt vmcnt(0)
.Lpf_skip_6:
	v_mov_b32_e32 v8, v254
	s_waitcnt lgkmcnt(0)
	s_barrier
	s_and_b64 vcc, exec, s[74:75]
	v_readfirstlane_b32 s8, v8
	s_cbranch_vccnz .LBB0_731
	s_ashr_i32 s3, s67, 31
	s_lshr_b32 s0, s3, 29
	s_add_i32 s5, s67, s0
	s_and_b32 s0, s5, -8
	s_sub_i32 s2, s67, s0
	s_cmp_gt_i32 s2, -1
	s_cbranch_scc0 .LBB0_710
	s_lshl_b32 s4, s2, 5
	s_ashr_i32 s0, s5, 3
	s_cbranch_execz .LBB0_711
	s_branch .LBB0_712
